# all six radix-16 FFT passes hand-written; LQ=6 and LQ=2 passes use hipcc's precomputed twiddle registers
# speedup vs baseline: 1.0107x; 1.0107x over previous
; template <bool INV> __device__ __forceinline__ void dft4(cf& a0, cf& a1, cf& a2, cf& a3) {
;     const cf t0 = cadd(a0, a2), t1 = csub(a0, a2), t2 = cadd(a1, a3), t3 = csub(a1, a3);
;     a0 = cadd(t0, t2); a2 = csub(t0, t2);
;     if (!INV) { a1 = {t1.x + t3.y, t1.y - t3.x}; a3 = {t1.x - t3.y, t1.y + t3.x}; }
;     else      { a1 = {t1.x - t3.y, t1.y + t3.x}; a3 = {t1.x + t3.y, t1.y - t3.x}; }
; }
; template <bool INV> __device__ __forceinline__ void dft16(cf (&a)[16]) {
; #pragma unroll
;     for (int n2 = 0; n2 < 4; ++n2) dft4<INV>(a[n2], a[4 + n2], a[8 + n2], a[12 + n2]);
; #pragma unroll
;     for (int k1 = 1; k1 < 4; ++k1)
; #pragma unroll
;         for (int n2 = 1; n2 < 4; ++n2) { const cf w = {W16C(n2 * k1), W16S(n2 * k1)};
;             a[4 * k1 + n2] = INV ? cmul(a[4 * k1 + n2], w) : cmulc(a[4 * k1 + n2], w); }
; #pragma unroll
;     for (int k1 = 0; k1 < 4; ++k1) dft4<INV>(a[4 * k1 + 0], a[4 * k1 + 1], a[4 * k1 + 2], a[4 * k1 + 3]);
; }
; template <bool INV, int LQ> __device__ __forceinline__ void fft_pass16(f32x2* X, int tid) {
;     constexpr int q = 1 << LQ, STR = q + 4 * (q >> 6);
; #pragma unroll 1
;     for (int gg = 0; gg < 2; ++gg) {
;         const int g = tid + 512 * gg, blk = g >> LQ, i = g & (q - 1), base = (blk << (LQ + 4)) + i;
;         f32x2* xb = X + fidx(base);
;         cf a[16];
; #pragma unroll
;         for (int j = 0; j < 16; ++j) { const f32x2 v = xb[j * STR]; a[j] = {v.x, v.y}; }
;         const float rev = (float)i * (1.f / (float)(16 << LQ));
;         const cf w1 = {__builtin_amdgcn_cosf(rev), __builtin_amdgcn_sinf(rev)};
;         if (!INV) {
;             dft16<false>(a);
;             cf w = w1;
; #pragma unroll
;             for (int k = 1; k < 16; ++k) { const int src = 4 * (k & 3) + (k >> 2);
;                 const cf y = cmulc(a[src], w); xb[k * STR] = (f32x2){y.x, y.y}; w = cmul(w, w1); }
.LBB0_281:
	v_add_u32_e32 v2, s93, v242
	v_lshrrev_b32_e32 v2, 4, v2
	v_and_b32_e32 v0, 63, v2
	v_lshrrev_b32_e32 v2, 6, v2
	v_lshl_add_u32 v1, v2, 10, v0
	v_lshrrev_b32_e32 v2, 6, v1
	v_lshl_add_u32 v1, v2, 2, v1
	v_lshlrev_b32_e32 v1, 3, v1
	ds_read_b64 v[10:11], v1
	ds_read_b64 v[12:13], v1 offset:544
	ds_read_b64 v[14:15], v1 offset:1088
	ds_read_b64 v[16:17], v1 offset:1632
	ds_read_b64 v[18:19], v1 offset:2176
	ds_read_b64 v[20:21], v1 offset:2720
	ds_read_b64 v[22:23], v1 offset:3264
	ds_read_b64 v[24:25], v1 offset:3808
	ds_read_b64 v[26:27], v1 offset:4352
	ds_read_b64 v[28:29], v1 offset:4896
	ds_read_b64 v[30:31], v1 offset:5440
	ds_read_b64 v[32:33], v1 offset:5984
	ds_read_b64 v[170:171], v1 offset:6528
	ds_read_b64 v[172:173], v1 offset:7072
	ds_read_b64 v[174:175], v1 offset:7616
	ds_read_b64 v[176:177], v1 offset:8160
	s_waitcnt lgkmcnt(0)
	v_add_f32_e32 v178, v10, v26
	v_add_f32_e32 v179, v11, v27
	v_sub_f32_e32 v180, v10, v26
	v_sub_f32_e32 v181, v11, v27
	v_add_f32_e32 v182, v18, v170
	v_add_f32_e32 v183, v19, v171
	v_sub_f32_e32 v184, v18, v170
	v_sub_f32_e32 v185, v19, v171
	v_add_f32_e32 v10, v178, v182
	v_add_f32_e32 v11, v179, v183
	v_sub_f32_e32 v26, v178, v182
	v_sub_f32_e32 v27, v179, v183
	v_add_f32_e32 v18, v180, v185
	v_sub_f32_e32 v19, v181, v184
	v_sub_f32_e32 v170, v180, v185
	v_add_f32_e32 v171, v181, v184
	v_add_f32_e32 v186, v12, v28
	v_add_f32_e32 v187, v13, v29
	v_sub_f32_e32 v188, v12, v28
	v_sub_f32_e32 v189, v13, v29
	v_add_f32_e32 v190, v20, v172
	v_add_f32_e32 v191, v21, v173
	v_sub_f32_e32 v192, v20, v172
	v_sub_f32_e32 v193, v21, v173
	v_add_f32_e32 v12, v186, v190
	v_add_f32_e32 v13, v187, v191
	v_sub_f32_e32 v28, v186, v190
	v_sub_f32_e32 v29, v187, v191
	v_add_f32_e32 v20, v188, v193
	v_sub_f32_e32 v21, v189, v192
	v_sub_f32_e32 v172, v188, v193
	v_add_f32_e32 v173, v189, v192
	v_add_f32_e32 v194, v14, v30
	v_add_f32_e32 v195, v15, v31
	v_sub_f32_e32 v196, v14, v30
	v_sub_f32_e32 v197, v15, v31
	v_add_f32_e32 v138, v22, v174
	v_add_f32_e32 v139, v23, v175
	v_sub_f32_e32 v140, v22, v174
	v_sub_f32_e32 v141, v23, v175
	v_add_f32_e32 v14, v194, v138
	v_add_f32_e32 v15, v195, v139
	v_sub_f32_e32 v30, v194, v138
	v_sub_f32_e32 v31, v195, v139
	v_add_f32_e32 v22, v196, v141
	v_sub_f32_e32 v23, v197, v140
	v_sub_f32_e32 v174, v196, v141
	v_add_f32_e32 v175, v197, v140
	v_add_f32_e32 v98, v16, v32
	v_add_f32_e32 v99, v17, v33
	v_sub_f32_e32 v178, v16, v32
	v_sub_f32_e32 v179, v17, v33
	v_add_f32_e32 v180, v24, v176
	v_add_f32_e32 v181, v25, v177
	v_sub_f32_e32 v182, v24, v176
	v_sub_f32_e32 v183, v25, v177
	v_add_f32_e32 v16, v98, v180
	v_add_f32_e32 v17, v99, v181
	v_sub_f32_e32 v32, v98, v180
	v_sub_f32_e32 v33, v99, v181
	v_add_f32_e32 v24, v178, v183
	v_sub_f32_e32 v25, v179, v182
	v_sub_f32_e32 v176, v178, v183
	v_add_f32_e32 v177, v179, v182
	v_mul_f32_e32 v184, s67, v20
	v_mul_f32_e32 v185, s67, v21
	v_fmac_f32_e32 v184, s66, v21
	v_fma_f32 v185, -v20, s66, v185
	v_add_f32_e32 v186, v22, v23
	v_sub_f32_e32 v187, v23, v22
	v_mul_f32_e32 v186, s70, v186
	v_mul_f32_e32 v187, s70, v187
	v_mul_f32_e32 v188, s66, v24
	v_mul_f32_e32 v189, s66, v25
	v_fmac_f32_e32 v188, s67, v25
	v_fma_f32 v189, -v24, s67, v189
	v_add_f32_e32 v190, v28, v29
	v_sub_f32_e32 v191, v29, v28
	v_mul_f32_e32 v190, s70, v190
	v_mul_f32_e32 v191, s70, v191
	v_mov_b32_e32 v192, v31
	v_xor_b32_e32 v193, 0x80000000, v30
	v_sub_f32_e32 v194, v33, v32
	v_add_f32_e32 v195, v32, v33
	v_mul_f32_e32 v194, s70, v194
	v_mul_f32_e32 v195, s71, v195
	v_mul_f32_e32 v196, s66, v172
	v_mul_f32_e32 v197, s66, v173
	v_fmac_f32_e32 v196, s67, v173
	v_fma_f32 v197, -v172, s67, v197
	v_sub_f32_e32 v138, v175, v174
	v_add_f32_e32 v139, v174, v175
	v_mul_f32_e32 v138, s70, v138
	v_mul_f32_e32 v139, s71, v139
	v_mul_f32_e32 v140, s67, v176
	v_mul_f32_e32 v141, s67, v177
	v_fmac_f32_e32 v140, s66, v177
	v_fma_f32 v141, -v176, s66, v141
	v_xor_b32_e32 v140, 0x80000000, v140
	v_xor_b32_e32 v141, 0x80000000, v141
	v_add_f32_e32 v98, v10, v14
	v_add_f32_e32 v99, v11, v15
	v_sub_f32_e32 v178, v10, v14
	v_sub_f32_e32 v179, v11, v15
	v_add_f32_e32 v180, v12, v16
	v_add_f32_e32 v181, v13, v17
	v_sub_f32_e32 v182, v12, v16
	v_sub_f32_e32 v183, v13, v17
	v_add_f32_e32 v10, v98, v180
	v_add_f32_e32 v11, v99, v181
	v_sub_f32_e32 v14, v98, v180
	v_sub_f32_e32 v15, v99, v181
	v_add_f32_e32 v12, v178, v183
	v_sub_f32_e32 v13, v179, v182
	v_sub_f32_e32 v16, v178, v183
	v_add_f32_e32 v17, v179, v182
	v_add_f32_e32 v20, v18, v186
	v_add_f32_e32 v21, v19, v187
	v_sub_f32_e32 v22, v18, v186
	v_sub_f32_e32 v23, v19, v187
	v_add_f32_e32 v24, v184, v188
	v_add_f32_e32 v25, v185, v189
	v_sub_f32_e32 v28, v184, v188
	v_sub_f32_e32 v29, v185, v189
	v_add_f32_e32 v18, v20, v24
	v_add_f32_e32 v19, v21, v25
	v_sub_f32_e32 v186, v20, v24
	v_sub_f32_e32 v187, v21, v25
	v_add_f32_e32 v184, v22, v29
	v_sub_f32_e32 v185, v23, v28
	v_sub_f32_e32 v188, v22, v29
	v_add_f32_e32 v189, v23, v28
	v_add_f32_e32 v30, v26, v192
	v_add_f32_e32 v31, v27, v193
	v_sub_f32_e32 v32, v26, v192
	v_sub_f32_e32 v33, v27, v193
	v_add_f32_e32 v172, v190, v194
	v_add_f32_e32 v173, v191, v195
	v_sub_f32_e32 v174, v190, v194
	v_sub_f32_e32 v175, v191, v195
	v_add_f32_e32 v26, v30, v172
	v_add_f32_e32 v27, v31, v173
	v_sub_f32_e32 v192, v30, v172
	v_sub_f32_e32 v193, v31, v173
	v_add_f32_e32 v190, v32, v175
	v_sub_f32_e32 v191, v33, v174
	v_sub_f32_e32 v194, v32, v175
	v_add_f32_e32 v195, v33, v174
	v_add_f32_e32 v176, v170, v138
	v_add_f32_e32 v177, v171, v139
	v_sub_f32_e32 v98, v170, v138
	v_sub_f32_e32 v99, v171, v139
	v_add_f32_e32 v178, v196, v140
	v_add_f32_e32 v179, v197, v141
	v_sub_f32_e32 v180, v196, v140
; template <bool INV> __device__ __forceinline__ void dft16(cf (&a)[16]) {
; #pragma unroll
;     for (int n2 = 0; n2 < 4; ++n2) dft4<INV>(a[n2], a[4 + n2], a[8 + n2], a[12 + n2]);
; #pragma unroll
;     for (int k1 = 1; k1 < 4; ++k1)
; #pragma unroll
;         for (int n2 = 1; n2 < 4; ++n2) { const cf w = {W16C(n2 * k1), W16S(n2 * k1)};
;             a[4 * k1 + n2] = INV ? cmul(a[4 * k1 + n2], w) : cmulc(a[4 * k1 + n2], w); }
; #pragma unroll
;     for (int k1 = 0; k1 < 4; ++k1) dft4<INV>(a[4 * k1 + 0], a[4 * k1 + 1], a[4 * k1 + 2], a[4 * k1 + 3]);
; }
; template <bool INV, int LQ> __device__ __forceinline__ void fft_pass16(f32x2* X, int tid) {
;     constexpr int q = 1 << LQ, STR = q + 4 * (q >> 6);
; #pragma unroll 1
;     for (int gg = 0; gg < 2; ++gg) {
;         const int g = tid + 512 * gg, blk = g >> LQ, i = g & (q - 1), base = (blk << (LQ + 4)) + i;
;         f32x2* xb = X + fidx(base);
;         cf a[16];
; #pragma unroll
;         for (int j = 0; j < 16; ++j) { const f32x2 v = xb[j * STR]; a[j] = {v.x, v.y}; }
;         const float rev = (float)i * (1.f / (float)(16 << LQ));
;         const cf w1 = {__builtin_amdgcn_cosf(rev), __builtin_amdgcn_sinf(rev)};
;         if (!INV) {
;             dft16<false>(a);
;             cf w = w1;
; #pragma unroll
;             for (int k = 1; k < 16; ++k) { const int src = 4 * (k & 3) + (k >> 2);
;                 const cf y = cmulc(a[src], w); xb[k * STR] = (f32x2){y.x, y.y}; w = cmul(w, w1); }
;             xb[0] = (f32x2){a[0].x, a[0].y};
	v_sub_f32_e32 v181, v197, v141
	v_add_f32_e32 v170, v176, v178
	v_add_f32_e32 v171, v177, v179
	v_sub_f32_e32 v138, v176, v178
	v_sub_f32_e32 v139, v177, v179
	v_add_f32_e32 v196, v98, v181
	v_sub_f32_e32 v197, v99, v180
	v_sub_f32_e32 v140, v98, v181
	v_add_f32_e32 v141, v99, v180
	ds_write_b64 v1, v[10:11]
	v_mul_f32_e32 v182, v18, v42
	v_mul_f32_e32 v183, v19, v42
	v_fmac_f32_e32 v182, v19, v44
	v_fma_f32 v183, -v18, v44, v183
	ds_write_b64 v1, v[182:183] offset:544
	v_mul_f32_e32 v20, v26, v46
	v_mul_f32_e32 v21, v27, v46
	v_fmac_f32_e32 v20, v27, v48
	v_fma_f32 v21, -v26, v48, v21
	ds_write_b64 v1, v[20:21] offset:1088
	v_mul_f32_e32 v22, v170, v50
	v_mul_f32_e32 v23, v171, v50
	v_fmac_f32_e32 v22, v171, v52
	v_fma_f32 v23, -v170, v52, v23
	ds_write_b64 v1, v[22:23] offset:1632
	v_mul_f32_e32 v24, v12, v54
	v_mul_f32_e32 v25, v13, v54
	v_fmac_f32_e32 v24, v13, v56
	v_fma_f32 v25, -v12, v56, v25
	ds_write_b64 v1, v[24:25] offset:2176
	v_mul_f32_e32 v28, v184, v58
	v_mul_f32_e32 v29, v185, v58
	v_fmac_f32_e32 v28, v185, v60
	v_fma_f32 v29, -v184, v60, v29
	ds_write_b64 v1, v[28:29] offset:2720
	v_mul_f32_e32 v30, v190, v62
	v_mul_f32_e32 v31, v191, v62
	v_fmac_f32_e32 v30, v191, v64
	v_fma_f32 v31, -v190, v64, v31
	ds_write_b64 v1, v[30:31] offset:3264
	v_mul_f32_e32 v32, v196, v66
	v_mul_f32_e32 v33, v197, v66
	v_fmac_f32_e32 v32, v197, v68
	v_fma_f32 v33, -v196, v68, v33
	ds_write_b64 v1, v[32:33] offset:3808
	v_mul_f32_e32 v172, v14, v70
	v_mul_f32_e32 v173, v15, v70
	v_fmac_f32_e32 v172, v15, v72
	v_fma_f32 v173, -v14, v72, v173
	ds_write_b64 v1, v[172:173] offset:4352
	v_mul_f32_e32 v174, v186, v74
	v_mul_f32_e32 v175, v187, v74
	v_fmac_f32_e32 v174, v187, v76
	v_fma_f32 v175, -v186, v76, v175
	ds_write_b64 v1, v[174:175] offset:4896
	v_mul_f32_e32 v176, v192, v78
	v_mul_f32_e32 v177, v193, v78
	v_fmac_f32_e32 v176, v193, v80
	v_fma_f32 v177, -v192, v80, v177
	ds_write_b64 v1, v[176:177] offset:5440
	v_mul_f32_e32 v98, v138, v82
	v_mul_f32_e32 v99, v139, v82
	v_fmac_f32_e32 v98, v139, v84
	v_fma_f32 v99, -v138, v84, v99
	ds_write_b64 v1, v[98:99] offset:5984
	v_mul_f32_e32 v178, v16, v86
	v_mul_f32_e32 v179, v17, v86
	v_fmac_f32_e32 v178, v17, v88
	v_fma_f32 v179, -v16, v88, v179
	ds_write_b64 v1, v[178:179] offset:6528
	v_mul_f32_e32 v180, v188, v90
	v_mul_f32_e32 v181, v189, v90
	v_fmac_f32_e32 v180, v189, v92
	v_fma_f32 v181, -v188, v92, v181
	ds_write_b64 v1, v[180:181] offset:7072
	v_mul_f32_e32 v18, v194, v94
	v_mul_f32_e32 v19, v195, v94
	v_fmac_f32_e32 v18, v195, v100
	v_fma_f32 v19, -v194, v100, v19
	ds_write_b64 v1, v[18:19] offset:7616
	v_mul_f32_e32 v182, v140, v102
	v_mul_f32_e32 v183, v141, v102
	v_fmac_f32_e32 v182, v141, v104
	v_fma_f32 v183, -v140, v104, v183
	ds_write_b64 v1, v[182:183] offset:8160
	s_mov_b32 s64, s67
	s_mov_b32 s65, s66
	s_mov_b32 s48, s25
	s_mov_b32 s49, s71
	s_mov_b32 s24, s71
	s_mov_b32 s94, s70
	s_mov_b32 s95, s66
	s_mov_b32 s61, s71
	s_movk_i32 s93, 0x2000
	s_and_b64 vcc, exec, s[38:39]
	s_mov_b64 s[38:39], 0
	s_cbranch_vccnz .LBB0_281
	s_mov_b32 s93, 0
	s_mov_b64 s[38:39], -1
	s_waitcnt lgkmcnt(0)
	s_barrier
.LBB0_283:
	v_add_u32_e32 v2, s93, v242
	v_lshrrev_b32_e32 v2, 4, v2
	v_and_b32_e32 v0, 3, v2
	v_lshrrev_b32_e32 v2, 2, v2
	v_lshl_add_u32 v1, v2, 6, v0
	v_lshrrev_b32_e32 v2, 6, v1
	v_lshl_add_u32 v1, v2, 2, v1
	v_lshlrev_b32_e32 v1, 3, v1
	ds_read_b64 v[10:11], v1
	ds_read_b64 v[12:13], v1 offset:32
	ds_read_b64 v[14:15], v1 offset:64
	ds_read_b64 v[16:17], v1 offset:96
	ds_read_b64 v[18:19], v1 offset:128
	ds_read_b64 v[20:21], v1 offset:160
	ds_read_b64 v[22:23], v1 offset:192
	ds_read_b64 v[24:25], v1 offset:224
	ds_read_b64 v[26:27], v1 offset:256
	ds_read_b64 v[28:29], v1 offset:288
	ds_read_b64 v[30:31], v1 offset:320
	ds_read_b64 v[32:33], v1 offset:352
	ds_read_b64 v[170:171], v1 offset:384
	ds_read_b64 v[172:173], v1 offset:416
	ds_read_b64 v[174:175], v1 offset:448
	ds_read_b64 v[176:177], v1 offset:480
	s_waitcnt lgkmcnt(0)
	v_add_f32_e32 v178, v10, v26
	v_add_f32_e32 v179, v11, v27
	v_sub_f32_e32 v180, v10, v26
	v_sub_f32_e32 v181, v11, v27
	v_add_f32_e32 v182, v18, v170
	v_add_f32_e32 v183, v19, v171
	v_sub_f32_e32 v184, v18, v170
	v_sub_f32_e32 v185, v19, v171
	v_add_f32_e32 v10, v178, v182
	v_add_f32_e32 v11, v179, v183
	v_sub_f32_e32 v26, v178, v182
	v_sub_f32_e32 v27, v179, v183
	v_add_f32_e32 v18, v180, v185
	v_sub_f32_e32 v19, v181, v184
	v_sub_f32_e32 v170, v180, v185
	v_add_f32_e32 v171, v181, v184
	v_add_f32_e32 v186, v12, v28
	v_add_f32_e32 v187, v13, v29
	v_sub_f32_e32 v188, v12, v28
	v_sub_f32_e32 v189, v13, v29
	v_add_f32_e32 v190, v20, v172
	v_add_f32_e32 v191, v21, v173
	v_sub_f32_e32 v192, v20, v172
	v_sub_f32_e32 v193, v21, v173
	v_add_f32_e32 v12, v186, v190
	v_add_f32_e32 v13, v187, v191
	v_sub_f32_e32 v28, v186, v190
	v_sub_f32_e32 v29, v187, v191
	v_add_f32_e32 v20, v188, v193
	v_sub_f32_e32 v21, v189, v192
	v_sub_f32_e32 v172, v188, v193
	v_add_f32_e32 v173, v189, v192
	v_add_f32_e32 v194, v14, v30
	v_add_f32_e32 v195, v15, v31
	v_sub_f32_e32 v196, v14, v30
	v_sub_f32_e32 v197, v15, v31
	v_add_f32_e32 v138, v22, v174
	v_add_f32_e32 v139, v23, v175
	v_sub_f32_e32 v140, v22, v174
	v_sub_f32_e32 v141, v23, v175
	v_add_f32_e32 v14, v194, v138
	v_add_f32_e32 v15, v195, v139
	v_sub_f32_e32 v30, v194, v138
	v_sub_f32_e32 v31, v195, v139
	v_add_f32_e32 v22, v196, v141
	v_sub_f32_e32 v23, v197, v140
	v_sub_f32_e32 v174, v196, v141
	v_add_f32_e32 v175, v197, v140
	v_add_f32_e32 v98, v16, v32
	v_add_f32_e32 v99, v17, v33
	v_sub_f32_e32 v178, v16, v32
	v_sub_f32_e32 v179, v17, v33
	v_add_f32_e32 v180, v24, v176
	v_add_f32_e32 v181, v25, v177
; template <bool INV> __device__ __forceinline__ void dft16(cf (&a)[16]) {
; #pragma unroll
;     for (int n2 = 0; n2 < 4; ++n2) dft4<INV>(a[n2], a[4 + n2], a[8 + n2], a[12 + n2]);
; #pragma unroll
;     for (int k1 = 1; k1 < 4; ++k1)
; #pragma unroll
;         for (int n2 = 1; n2 < 4; ++n2) { const cf w = {W16C(n2 * k1), W16S(n2 * k1)};
;             a[4 * k1 + n2] = INV ? cmul(a[4 * k1 + n2], w) : cmulc(a[4 * k1 + n2], w); }
; #pragma unroll
;     for (int k1 = 0; k1 < 4; ++k1) dft4<INV>(a[4 * k1 + 0], a[4 * k1 + 1], a[4 * k1 + 2], a[4 * k1 + 3]);
; }
; template <bool INV, int LQ> __device__ __forceinline__ void fft_pass16(f32x2* X, int tid) {
;     constexpr int q = 1 << LQ, STR = q + 4 * (q >> 6);
; #pragma unroll 1
;     for (int gg = 0; gg < 2; ++gg) {
;         const int g = tid + 512 * gg, blk = g >> LQ, i = g & (q - 1), base = (blk << (LQ + 4)) + i;
;         f32x2* xb = X + fidx(base);
;         cf a[16];
; #pragma unroll
;         for (int j = 0; j < 16; ++j) { const f32x2 v = xb[j * STR]; a[j] = {v.x, v.y}; }
;         const float rev = (float)i * (1.f / (float)(16 << LQ));
;         const cf w1 = {__builtin_amdgcn_cosf(rev), __builtin_amdgcn_sinf(rev)};
;         if (!INV) {
;             dft16<false>(a);
;             cf w = w1;
; #pragma unroll
;             for (int k = 1; k < 16; ++k) { const int src = 4 * (k & 3) + (k >> 2);
;                 const cf y = cmulc(a[src], w); xb[k * STR] = (f32x2){y.x, y.y}; w = cmul(w, w1); }
;             xb[0] = (f32x2){a[0].x, a[0].y};
	v_sub_f32_e32 v182, v24, v176
	v_sub_f32_e32 v183, v25, v177
	v_add_f32_e32 v16, v98, v180
	v_add_f32_e32 v17, v99, v181
	v_sub_f32_e32 v32, v98, v180
	v_sub_f32_e32 v33, v99, v181
	v_add_f32_e32 v24, v178, v183
	v_sub_f32_e32 v25, v179, v182
	v_sub_f32_e32 v176, v178, v183
	v_add_f32_e32 v177, v179, v182
	v_mul_f32_e32 v184, s67, v20
	v_mul_f32_e32 v185, s67, v21
	v_fmac_f32_e32 v184, s66, v21
	v_fma_f32 v185, -v20, s66, v185
	v_add_f32_e32 v186, v22, v23
	v_sub_f32_e32 v187, v23, v22
	v_mul_f32_e32 v186, s70, v186
	v_mul_f32_e32 v187, s70, v187
	v_mul_f32_e32 v188, s66, v24
	v_mul_f32_e32 v189, s66, v25
	v_fmac_f32_e32 v188, s67, v25
	v_fma_f32 v189, -v24, s67, v189
	v_add_f32_e32 v190, v28, v29
	v_sub_f32_e32 v191, v29, v28
	v_mul_f32_e32 v190, s70, v190
	v_mul_f32_e32 v191, s70, v191
	v_mov_b32_e32 v192, v31
	v_xor_b32_e32 v193, 0x80000000, v30
	v_sub_f32_e32 v194, v33, v32
	v_add_f32_e32 v195, v32, v33
	v_mul_f32_e32 v194, s70, v194
	v_mul_f32_e32 v195, s71, v195
	v_mul_f32_e32 v196, s66, v172
	v_mul_f32_e32 v197, s66, v173
	v_fmac_f32_e32 v196, s67, v173
	v_fma_f32 v197, -v172, s67, v197
	v_sub_f32_e32 v138, v175, v174
	v_add_f32_e32 v139, v174, v175
	v_mul_f32_e32 v138, s70, v138
	v_mul_f32_e32 v139, s71, v139
	v_mul_f32_e32 v140, s67, v176
	v_mul_f32_e32 v141, s67, v177
	v_fmac_f32_e32 v140, s66, v177
	v_fma_f32 v141, -v176, s66, v141
	v_xor_b32_e32 v140, 0x80000000, v140
	v_xor_b32_e32 v141, 0x80000000, v141
	v_add_f32_e32 v98, v10, v14
	v_add_f32_e32 v99, v11, v15
	v_sub_f32_e32 v178, v10, v14
	v_sub_f32_e32 v179, v11, v15
	v_add_f32_e32 v180, v12, v16
	v_add_f32_e32 v181, v13, v17
	v_sub_f32_e32 v182, v12, v16
	v_sub_f32_e32 v183, v13, v17
	v_add_f32_e32 v10, v98, v180
	v_add_f32_e32 v11, v99, v181
	v_sub_f32_e32 v14, v98, v180
	v_sub_f32_e32 v15, v99, v181
	v_add_f32_e32 v12, v178, v183
	v_sub_f32_e32 v13, v179, v182
	v_sub_f32_e32 v16, v178, v183
	v_add_f32_e32 v17, v179, v182
	v_add_f32_e32 v20, v18, v186
	v_add_f32_e32 v21, v19, v187
	v_sub_f32_e32 v22, v18, v186
	v_sub_f32_e32 v23, v19, v187
	v_add_f32_e32 v24, v184, v188
	v_add_f32_e32 v25, v185, v189
	v_sub_f32_e32 v28, v184, v188
	v_sub_f32_e32 v29, v185, v189
	v_add_f32_e32 v18, v20, v24
	v_add_f32_e32 v19, v21, v25
	v_sub_f32_e32 v186, v20, v24
	v_sub_f32_e32 v187, v21, v25
	v_add_f32_e32 v184, v22, v29
	v_sub_f32_e32 v185, v23, v28
	v_sub_f32_e32 v188, v22, v29
	v_add_f32_e32 v189, v23, v28
	v_add_f32_e32 v30, v26, v192
	v_add_f32_e32 v31, v27, v193
	v_sub_f32_e32 v32, v26, v192
	v_sub_f32_e32 v33, v27, v193
	v_add_f32_e32 v172, v190, v194
	v_add_f32_e32 v173, v191, v195
	v_sub_f32_e32 v174, v190, v194
	v_sub_f32_e32 v175, v191, v195
	v_add_f32_e32 v26, v30, v172
	v_add_f32_e32 v27, v31, v173
	v_sub_f32_e32 v192, v30, v172
	v_sub_f32_e32 v193, v31, v173
	v_add_f32_e32 v190, v32, v175
	v_sub_f32_e32 v191, v33, v174
	v_sub_f32_e32 v194, v32, v175
	v_add_f32_e32 v195, v33, v174
	v_add_f32_e32 v176, v170, v138
	v_add_f32_e32 v177, v171, v139
	v_sub_f32_e32 v98, v170, v138
	v_sub_f32_e32 v99, v171, v139
	v_add_f32_e32 v178, v196, v140
	v_add_f32_e32 v179, v197, v141
	v_sub_f32_e32 v180, v196, v140
	v_sub_f32_e32 v181, v197, v141
	v_add_f32_e32 v170, v176, v178
	v_add_f32_e32 v171, v177, v179
	v_sub_f32_e32 v138, v176, v178
	v_sub_f32_e32 v139, v177, v179
	v_add_f32_e32 v196, v98, v181
	v_sub_f32_e32 v197, v99, v180
	v_sub_f32_e32 v140, v98, v181
	v_add_f32_e32 v141, v99, v180
	ds_write_b64 v1, v[10:11]
	v_mul_f32_e32 v182, v18, v108
	v_mul_f32_e32 v183, v19, v108
	v_fmac_f32_e32 v182, v19, v106
	v_fma_f32 v183, -v18, v106, v183
	ds_write_b64 v1, v[182:183] offset:32
	v_mul_f32_e32 v20, v26, v110
	v_mul_f32_e32 v21, v27, v110
	v_fmac_f32_e32 v20, v27, v112
	v_fma_f32 v21, -v26, v112, v21
	ds_write_b64 v1, v[20:21] offset:64
	v_mul_f32_e32 v22, v170, v114
	v_mul_f32_e32 v23, v171, v114
	v_fmac_f32_e32 v22, v171, v116
	v_fma_f32 v23, -v170, v116, v23
	ds_write_b64 v1, v[22:23] offset:96
	v_mul_f32_e32 v24, v12, v118
	v_mul_f32_e32 v25, v13, v118
	v_fmac_f32_e32 v24, v13, v120
	v_fma_f32 v25, -v12, v120, v25
	ds_write_b64 v1, v[24:25] offset:128
	v_mul_f32_e32 v28, v184, v122
	v_mul_f32_e32 v29, v185, v122
	v_fmac_f32_e32 v28, v185, v124
	v_fma_f32 v29, -v184, v124, v29
	ds_write_b64 v1, v[28:29] offset:160
	v_mul_f32_e32 v30, v190, v126
	v_mul_f32_e32 v31, v191, v126
	v_fmac_f32_e32 v30, v191, v128
	v_fma_f32 v31, -v190, v128, v31
	ds_write_b64 v1, v[30:31] offset:192
	v_mul_f32_e32 v32, v196, v130
	v_mul_f32_e32 v33, v197, v130
	v_fmac_f32_e32 v32, v197, v132
	v_fma_f32 v33, -v196, v132, v33
	ds_write_b64 v1, v[32:33] offset:224
	v_mul_f32_e32 v172, v14, v134
	v_mul_f32_e32 v173, v15, v134
	v_fmac_f32_e32 v172, v15, v136
	v_fma_f32 v173, -v14, v136, v173
	ds_write_b64 v1, v[172:173] offset:256
	v_mul_f32_e32 v174, v186, v142
	v_mul_f32_e32 v175, v187, v142
	v_fmac_f32_e32 v174, v187, v144
	v_fma_f32 v175, -v186, v144, v175
	ds_write_b64 v1, v[174:175] offset:288
	v_mul_f32_e32 v176, v192, v146
	v_mul_f32_e32 v177, v193, v146
	v_fmac_f32_e32 v176, v193, v148
	v_fma_f32 v177, -v192, v148, v177
	ds_write_b64 v1, v[176:177] offset:320
	v_mul_f32_e32 v98, v138, v150
	v_mul_f32_e32 v99, v139, v150
	v_fmac_f32_e32 v98, v139, v152
	v_fma_f32 v99, -v138, v152, v99
	ds_write_b64 v1, v[98:99] offset:352
	v_mul_f32_e32 v178, v16, v154
	v_mul_f32_e32 v179, v17, v154
	v_fmac_f32_e32 v178, v17, v156
	v_fma_f32 v179, -v16, v156, v179
	ds_write_b64 v1, v[178:179] offset:384
	v_mul_f32_e32 v180, v188, v158
	v_mul_f32_e32 v181, v189, v158
	v_fmac_f32_e32 v180, v189, v160
	v_fma_f32 v181, -v188, v160, v181
	ds_write_b64 v1, v[180:181] offset:416
	v_mul_f32_e32 v18, v194, v162
	v_mul_f32_e32 v19, v195, v162
	v_fmac_f32_e32 v18, v195, v164
	v_fma_f32 v19, -v194, v164, v19
	ds_write_b64 v1, v[18:19] offset:448
	v_mul_f32_e32 v182, v140, v166
	v_mul_f32_e32 v183, v141, v166
	v_fmac_f32_e32 v182, v141, v168
	v_fma_f32 v183, -v140, v168, v183
	ds_write_b64 v1, v[182:183] offset:480
	s_mov_b32 s64, s67
	s_mov_b32 s65, s66
	s_mov_b32 s48, s25
	s_mov_b32 s49, s71
	s_mov_b32 s24, s71
	s_mov_b32 s94, s70
	s_mov_b32 s95, s66
	s_mov_b32 s61, s71
	s_movk_i32 s93, 0x2000
	s_and_b64 vcc, exec, s[38:39]
	s_mov_b64 s[38:39], 0
	s_cbranch_vccnz .LBB0_283
	v_cndmask_b32_e64 v0, 0, 1, s[0:1]
	v_cmp_ne_u32_e64 s[38:39], 1, v0
	s_andn2_b64 vcc, exec, s[0:1]
	s_mov_b64 s[0:1], -1
	s_mov_b32 s61, s79
	s_waitcnt lgkmcnt(0)
	s_barrier
	s_cbranch_vccnz .LBB0_288
	s_mov_b32 s0, 0
	v_mov_b32_e32 v0, v245

; template <bool INV> __device__ __forceinline__ void dft16(cf (&a)[16]) {
; #pragma unroll
;     for (int n2 = 0; n2 < 4; ++n2) dft4<INV>(a[n2], a[4 + n2], a[8 + n2], a[12 + n2]);
; #pragma unroll
;     for (int k1 = 1; k1 < 4; ++k1)
; #pragma unroll
;         for (int n2 = 1; n2 < 4; ++n2) { const cf w = {W16C(n2 * k1), W16S(n2 * k1)};
;             a[4 * k1 + n2] = INV ? cmul(a[4 * k1 + n2], w) : cmulc(a[4 * k1 + n2], w); }
; #pragma unroll
;     for (int k1 = 0; k1 < 4; ++k1) dft4<INV>(a[4 * k1 + 0], a[4 * k1 + 1], a[4 * k1 + 2], a[4 * k1 + 3]);
; }
; template <bool INV, int LQ> __device__ __forceinline__ void fft_pass16(f32x2* X, int tid) {
;     constexpr int q = 1 << LQ, STR = q + 4 * (q >> 6);
; #pragma unroll 1
;     for (int gg = 0; gg < 2; ++gg) {
;         const int g = tid + 512 * gg, blk = g >> LQ, i = g & (q - 1), base = (blk << (LQ + 4)) + i;
;         f32x2* xb = X + fidx(base);
;         cf a[16];
; #pragma unroll
;         for (int j = 0; j < 16; ++j) { const f32x2 v = xb[j * STR]; a[j] = {v.x, v.y}; }
;         const float rev = (float)i * (1.f / (float)(16 << LQ));
;         const cf w1 = {__builtin_amdgcn_cosf(rev), __builtin_amdgcn_sinf(rev)};
;         if (!INV) {
;             dft16<false>(a);
;             cf w = w1;
; #pragma unroll
;             for (int k = 1; k < 16; ++k) { const int src = 4 * (k & 3) + (k >> 2);
;                 const cf y = cmulc(a[src], w); xb[k * STR] = (f32x2){y.x, y.y}; w = cmul(w, w1); }
;             xb[0] = (f32x2){a[0].x, a[0].y};
;         } else {
;             cf w = w1;
; #pragma unroll
;             for (int k = 1; k < 16; ++k) { a[k] = cmul(a[k], w); w = cmul(w, w1); }
;             dft16<true>(a);
; #pragma unroll
;             for (int k = 0; k < 16; ++k) { const int src = 4 * (k & 3) + (k >> 2); xb[k * STR] = (f32x2){a[src].x, a[src].y}; }
;         }
.LBB0_292:
	v_add_u32_e32 v2, s24, v242
	v_lshrrev_b32_e32 v2, 4, v2
	v_and_b32_e32 v0, 3, v2
	v_lshrrev_b32_e32 v2, 2, v2
	v_lshl_add_u32 v1, v2, 6, v0
	v_lshrrev_b32_e32 v2, 6, v1
	v_lshl_add_u32 v1, v2, 2, v1
	v_lshlrev_b32_e32 v1, 3, v1
	ds_read_b64 v[10:11], v1
	ds_read_b64 v[12:13], v1 offset:32
	ds_read_b64 v[14:15], v1 offset:64
	ds_read_b64 v[16:17], v1 offset:96
	ds_read_b64 v[18:19], v1 offset:128
	ds_read_b64 v[20:21], v1 offset:160
	ds_read_b64 v[22:23], v1 offset:192
	ds_read_b64 v[24:25], v1 offset:224
	ds_read_b64 v[26:27], v1 offset:256
	ds_read_b64 v[28:29], v1 offset:288
	ds_read_b64 v[30:31], v1 offset:320
	ds_read_b64 v[32:33], v1 offset:352
	ds_read_b64 v[170:171], v1 offset:384
	ds_read_b64 v[172:173], v1 offset:416
	ds_read_b64 v[174:175], v1 offset:448
	ds_read_b64 v[176:177], v1 offset:480
	s_waitcnt lgkmcnt(0)
	v_mul_f32_e32 v178, v12, v108
	v_mul_f32_e32 v179, v12, v106
	v_fma_f32 v178, -v13, v106, v178
	v_fmac_f32_e32 v179, v13, v108
	v_mul_f32_e32 v180, v14, v110
	v_mul_f32_e32 v181, v14, v112
	v_fma_f32 v180, -v15, v112, v180
	v_fmac_f32_e32 v181, v15, v110
	v_mul_f32_e32 v182, v16, v114
	v_mul_f32_e32 v183, v16, v116
	v_fma_f32 v182, -v17, v116, v182
	v_fmac_f32_e32 v183, v17, v114
	v_mul_f32_e32 v184, v18, v118
	v_mul_f32_e32 v185, v18, v120
	v_fma_f32 v184, -v19, v120, v184
	v_fmac_f32_e32 v185, v19, v118
	v_mul_f32_e32 v186, v20, v122
	v_mul_f32_e32 v187, v20, v124
	v_fma_f32 v186, -v21, v124, v186
	v_fmac_f32_e32 v187, v21, v122
	v_mul_f32_e32 v188, v22, v126
	v_mul_f32_e32 v189, v22, v128
	v_fma_f32 v188, -v23, v128, v188
	v_fmac_f32_e32 v189, v23, v126
	v_mul_f32_e32 v190, v24, v130
	v_mul_f32_e32 v191, v24, v132
	v_fma_f32 v190, -v25, v132, v190
	v_fmac_f32_e32 v191, v25, v130
	v_mul_f32_e32 v192, v26, v134
	v_mul_f32_e32 v193, v26, v136
	v_fma_f32 v192, -v27, v136, v192
	v_fmac_f32_e32 v193, v27, v134
	v_mul_f32_e32 v194, v28, v142
	v_mul_f32_e32 v195, v28, v144
	v_fma_f32 v194, -v29, v144, v194
	v_fmac_f32_e32 v195, v29, v142
	v_mul_f32_e32 v196, v30, v146
	v_mul_f32_e32 v197, v30, v148
	v_fma_f32 v196, -v31, v148, v196
	v_fmac_f32_e32 v197, v31, v146
	v_mul_f32_e32 v138, v32, v150
	v_mul_f32_e32 v139, v32, v152
	v_fma_f32 v138, -v33, v152, v138
	v_fmac_f32_e32 v139, v33, v150
	v_mul_f32_e32 v140, v170, v154
	v_mul_f32_e32 v141, v170, v156
	v_fma_f32 v140, -v171, v156, v140
	v_fmac_f32_e32 v141, v171, v154
	v_mul_f32_e32 v98, v172, v158
	v_mul_f32_e32 v99, v172, v160
	v_fma_f32 v98, -v173, v160, v98
	v_fmac_f32_e32 v99, v173, v158
	v_mul_f32_e32 v12, v174, v162
	v_mul_f32_e32 v13, v174, v164
	v_fma_f32 v12, -v175, v164, v12
	v_fmac_f32_e32 v13, v175, v162
	v_mul_f32_e32 v14, v176, v166
	v_mul_f32_e32 v15, v176, v168
	v_fma_f32 v14, -v177, v168, v14
	v_fmac_f32_e32 v15, v177, v166
	v_add_f32_e32 v16, v10, v192
	v_add_f32_e32 v17, v11, v193
	v_sub_f32_e32 v18, v10, v192
	v_sub_f32_e32 v19, v11, v193
	v_add_f32_e32 v20, v184, v140
	v_add_f32_e32 v21, v185, v141
	v_sub_f32_e32 v22, v184, v140
	v_sub_f32_e32 v23, v185, v141
	v_add_f32_e32 v10, v16, v20
	v_add_f32_e32 v11, v17, v21
	v_sub_f32_e32 v192, v16, v20
	v_sub_f32_e32 v193, v17, v21
	v_sub_f32_e32 v184, v18, v23
	v_add_f32_e32 v185, v19, v22
	v_add_f32_e32 v140, v18, v23
	v_sub_f32_e32 v141, v19, v22
	v_add_f32_e32 v24, v178, v194
	v_add_f32_e32 v25, v179, v195
	v_sub_f32_e32 v26, v178, v194
	v_sub_f32_e32 v27, v179, v195
	v_add_f32_e32 v28, v186, v98
	v_add_f32_e32 v29, v187, v99
	v_sub_f32_e32 v30, v186, v98
	v_sub_f32_e32 v31, v187, v99
	v_add_f32_e32 v178, v24, v28
	v_add_f32_e32 v179, v25, v29
	v_sub_f32_e32 v194, v24, v28
	v_sub_f32_e32 v195, v25, v29
	v_sub_f32_e32 v186, v26, v31
	v_add_f32_e32 v187, v27, v30
	v_add_f32_e32 v98, v26, v31
	v_sub_f32_e32 v99, v27, v30
	v_add_f32_e32 v32, v180, v196
	v_add_f32_e32 v33, v181, v197
	v_sub_f32_e32 v170, v180, v196
	v_sub_f32_e32 v171, v181, v197
	v_add_f32_e32 v172, v188, v12
	v_add_f32_e32 v173, v189, v13
	v_sub_f32_e32 v174, v188, v12
	v_sub_f32_e32 v175, v189, v13
	v_add_f32_e32 v180, v32, v172
	v_add_f32_e32 v181, v33, v173
	v_sub_f32_e32 v196, v32, v172
	v_sub_f32_e32 v197, v33, v173
	v_sub_f32_e32 v188, v170, v175
	v_add_f32_e32 v189, v171, v174
	v_add_f32_e32 v12, v170, v175
	v_sub_f32_e32 v13, v171, v174
	v_add_f32_e32 v176, v182, v138
	v_add_f32_e32 v177, v183, v139
	v_sub_f32_e32 v16, v182, v138
	v_sub_f32_e32 v17, v183, v139
	v_add_f32_e32 v18, v190, v14
	v_add_f32_e32 v19, v191, v15
	v_sub_f32_e32 v20, v190, v14
	v_sub_f32_e32 v21, v191, v15
	v_add_f32_e32 v182, v176, v18
	v_add_f32_e32 v183, v177, v19
	v_sub_f32_e32 v138, v176, v18
	v_sub_f32_e32 v139, v177, v19
	v_sub_f32_e32 v190, v16, v21
	v_add_f32_e32 v191, v17, v20
	v_add_f32_e32 v14, v16, v21
	v_sub_f32_e32 v15, v17, v20
	v_mul_f32_e32 v22, s67, v186
	v_mul_f32_e32 v23, s67, v187
	v_fma_f32 v22, -v187, s66, v22
	v_fmac_f32_e32 v23, s66, v186
	v_sub_f32_e32 v24, v188, v189
	v_add_f32_e32 v25, v188, v189
	v_mul_f32_e32 v24, s70, v24
	v_mul_f32_e32 v25, s70, v25
	v_mul_f32_e32 v26, s66, v190
	v_mul_f32_e32 v27, s66, v191
	v_fma_f32 v26, -v191, s67, v26
	v_fmac_f32_e32 v27, s67, v190
	v_sub_f32_e32 v28, v194, v195
	v_add_f32_e32 v29, v194, v195
	v_mul_f32_e32 v28, s70, v28
	v_mul_f32_e32 v29, s70, v29
	v_xor_b32_e32 v30, 0x80000000, v197
	v_mov_b32_e32 v31, v196
	v_add_f32_e32 v32, v138, v139
	v_sub_f32_e32 v33, v138, v139
	v_mul_f32_e32 v32, s71, v32
	v_mul_f32_e32 v33, s70, v33
	v_mul_f32_e32 v170, s66, v98
	v_mul_f32_e32 v171, s66, v99
	v_fma_f32 v170, -v99, s67, v170
	v_fmac_f32_e32 v171, s67, v98
	v_add_f32_e32 v172, v12, v13
	v_sub_f32_e32 v173, v12, v13
	v_mul_f32_e32 v172, s71, v172
	v_mul_f32_e32 v173, s70, v173
; template <bool INV> __device__ __forceinline__ void dft16(cf (&a)[16]) {
; #pragma unroll
;     for (int n2 = 0; n2 < 4; ++n2) dft4<INV>(a[n2], a[4 + n2], a[8 + n2], a[12 + n2]);
; #pragma unroll
;     for (int k1 = 1; k1 < 4; ++k1)
; #pragma unroll
;         for (int n2 = 1; n2 < 4; ++n2) { const cf w = {W16C(n2 * k1), W16S(n2 * k1)};
;             a[4 * k1 + n2] = INV ? cmul(a[4 * k1 + n2], w) : cmulc(a[4 * k1 + n2], w); }
; #pragma unroll
;     for (int k1 = 0; k1 < 4; ++k1) dft4<INV>(a[4 * k1 + 0], a[4 * k1 + 1], a[4 * k1 + 2], a[4 * k1 + 3]);
; }
; template <bool INV, int LQ> __device__ __forceinline__ void fft_pass16(f32x2* X, int tid) {
;     constexpr int q = 1 << LQ, STR = q + 4 * (q >> 6);
; #pragma unroll 1
;     for (int gg = 0; gg < 2; ++gg) {
;         const int g = tid + 512 * gg, blk = g >> LQ, i = g & (q - 1), base = (blk << (LQ + 4)) + i;
;         f32x2* xb = X + fidx(base);
;         cf a[16];
; #pragma unroll
;         for (int j = 0; j < 16; ++j) { const f32x2 v = xb[j * STR]; a[j] = {v.x, v.y}; }
;         const float rev = (float)i * (1.f / (float)(16 << LQ));
;         const cf w1 = {__builtin_amdgcn_cosf(rev), __builtin_amdgcn_sinf(rev)};
;         if (!INV) {
;             dft16<false>(a);
;             cf w = w1;
; #pragma unroll
;             for (int k = 1; k < 16; ++k) { const int src = 4 * (k & 3) + (k >> 2);
;                 const cf y = cmulc(a[src], w); xb[k * STR] = (f32x2){y.x, y.y}; w = cmul(w, w1); }
;             xb[0] = (f32x2){a[0].x, a[0].y};
;         } else {
;             cf w = w1;
; #pragma unroll
;             for (int k = 1; k < 16; ++k) { a[k] = cmul(a[k], w); w = cmul(w, w1); }
;             dft16<true>(a);
; #pragma unroll
;             for (int k = 0; k < 16; ++k) { const int src = 4 * (k & 3) + (k >> 2); xb[k * STR] = (f32x2){a[src].x, a[src].y}; }
;         }
	v_mul_f32_e32 v174, s67, v14
	v_mul_f32_e32 v175, s67, v15
	v_fma_f32 v174, -v15, s66, v174
	v_fmac_f32_e32 v175, s66, v14
	v_xor_b32_e32 v174, 0x80000000, v174
	v_xor_b32_e32 v175, 0x80000000, v175
	v_add_f32_e32 v176, v10, v180
	v_add_f32_e32 v177, v11, v181
	v_sub_f32_e32 v16, v10, v180
	v_sub_f32_e32 v17, v11, v181
	v_add_f32_e32 v18, v178, v182
	v_add_f32_e32 v19, v179, v183
	v_sub_f32_e32 v20, v178, v182
	v_sub_f32_e32 v21, v179, v183
	v_add_f32_e32 v10, v176, v18
	v_add_f32_e32 v11, v177, v19
	v_sub_f32_e32 v180, v176, v18
	v_sub_f32_e32 v181, v177, v19
	v_sub_f32_e32 v178, v16, v21
	v_add_f32_e32 v179, v17, v20
	v_add_f32_e32 v182, v16, v21
	v_sub_f32_e32 v183, v17, v20
	v_add_f32_e32 v186, v184, v24
	v_add_f32_e32 v187, v185, v25
	v_sub_f32_e32 v188, v184, v24
	v_sub_f32_e32 v189, v185, v25
	v_add_f32_e32 v190, v22, v26
	v_add_f32_e32 v191, v23, v27
	v_sub_f32_e32 v194, v22, v26
	v_sub_f32_e32 v195, v23, v27
	v_add_f32_e32 v184, v186, v190
	v_add_f32_e32 v185, v187, v191
	v_sub_f32_e32 v24, v186, v190
	v_sub_f32_e32 v25, v187, v191
	v_sub_f32_e32 v22, v188, v195
	v_add_f32_e32 v23, v189, v194
	v_add_f32_e32 v26, v188, v195
	v_sub_f32_e32 v27, v189, v194
	v_add_f32_e32 v196, v192, v30
	v_add_f32_e32 v197, v193, v31
	v_sub_f32_e32 v138, v192, v30
	v_sub_f32_e32 v139, v193, v31
	v_add_f32_e32 v98, v28, v32
	v_add_f32_e32 v99, v29, v33
	v_sub_f32_e32 v12, v28, v32
	v_sub_f32_e32 v13, v29, v33
	v_add_f32_e32 v192, v196, v98
	v_add_f32_e32 v193, v197, v99
	v_sub_f32_e32 v30, v196, v98
	v_sub_f32_e32 v31, v197, v99
	v_sub_f32_e32 v28, v138, v13
	v_add_f32_e32 v29, v139, v12
	v_add_f32_e32 v32, v138, v13
	v_sub_f32_e32 v33, v139, v12
	v_add_f32_e32 v14, v140, v172
	v_add_f32_e32 v15, v141, v173
	v_sub_f32_e32 v176, v140, v172
	v_sub_f32_e32 v177, v141, v173
	v_add_f32_e32 v16, v170, v174
	v_add_f32_e32 v17, v171, v175
	v_sub_f32_e32 v18, v170, v174
	v_sub_f32_e32 v19, v171, v175
	v_add_f32_e32 v140, v14, v16
	v_add_f32_e32 v141, v15, v17
	v_sub_f32_e32 v172, v14, v16
	v_sub_f32_e32 v173, v15, v17
	v_sub_f32_e32 v170, v176, v19
	v_add_f32_e32 v171, v177, v18
	v_add_f32_e32 v174, v176, v19
	v_sub_f32_e32 v175, v177, v18
	ds_write_b64 v1, v[10:11]
	ds_write_b64 v1, v[184:185] offset:32
	ds_write_b64 v1, v[192:193] offset:64
	ds_write_b64 v1, v[140:141] offset:96
	ds_write_b64 v1, v[178:179] offset:128
	ds_write_b64 v1, v[22:23] offset:160
	ds_write_b64 v1, v[28:29] offset:192
	ds_write_b64 v1, v[170:171] offset:224
	ds_write_b64 v1, v[180:181] offset:256
	ds_write_b64 v1, v[24:25] offset:288
	ds_write_b64 v1, v[30:31] offset:320
	ds_write_b64 v1, v[172:173] offset:352
	ds_write_b64 v1, v[182:183] offset:384
	ds_write_b64 v1, v[26:27] offset:416
	ds_write_b64 v1, v[32:33] offset:448
	ds_write_b64 v1, v[174:175] offset:480
	s_mov_b32 s38, s67
	s_mov_b32 s39, s66
	s_mov_b32 s40, s70
	s_mov_b32 s41, s66
	s_mov_b32 s38, s71
	s_mov_b32 s39, s67
	s_mov_b32 s40, s25
	s_mov_b32 s41, s71
	s_movk_i32 s24, 0x2000
	s_and_b64 vcc, exec, s[0:1]
	s_mov_b64 s[0:1], 0
	s_cbranch_vccnz .LBB0_292
	s_mov_b32 s24, 0
	s_mov_b64 s[0:1], -1
	s_waitcnt lgkmcnt(0)
	s_barrier
.LBB0_294:
	v_add_u32_e32 v2, s24, v242
	v_lshrrev_b32_e32 v2, 4, v2
	v_and_b32_e32 v0, 63, v2
	v_lshrrev_b32_e32 v2, 6, v2
	v_lshl_add_u32 v1, v2, 10, v0
	v_lshrrev_b32_e32 v2, 6, v1
	v_lshl_add_u32 v1, v2, 2, v1
	v_lshlrev_b32_e32 v1, 3, v1
	ds_read_b64 v[10:11], v1
	ds_read_b64 v[12:13], v1 offset:544
	ds_read_b64 v[14:15], v1 offset:1088
	ds_read_b64 v[16:17], v1 offset:1632
	ds_read_b64 v[18:19], v1 offset:2176
	ds_read_b64 v[20:21], v1 offset:2720
	ds_read_b64 v[22:23], v1 offset:3264
	ds_read_b64 v[24:25], v1 offset:3808
	ds_read_b64 v[26:27], v1 offset:4352
	ds_read_b64 v[28:29], v1 offset:4896
	ds_read_b64 v[30:31], v1 offset:5440
	ds_read_b64 v[32:33], v1 offset:5984
	ds_read_b64 v[106:107], v1 offset:6528
	ds_read_b64 v[108:109], v1 offset:7072
	ds_read_b64 v[110:111], v1 offset:7616
	ds_read_b64 v[112:113], v1 offset:8160
	s_waitcnt lgkmcnt(0)
	v_mul_f32_e32 v114, v12, v42
	v_mul_f32_e32 v115, v12, v44
	v_fma_f32 v114, -v13, v44, v114
	v_fmac_f32_e32 v115, v13, v42
	v_mul_f32_e32 v116, v14, v46
	v_mul_f32_e32 v117, v14, v48
	v_fma_f32 v116, -v15, v48, v116
	v_fmac_f32_e32 v117, v15, v46
	v_mul_f32_e32 v118, v16, v50
	v_mul_f32_e32 v119, v16, v52
	v_fma_f32 v118, -v17, v52, v118
	v_fmac_f32_e32 v119, v17, v50
	v_mul_f32_e32 v120, v18, v54
	v_mul_f32_e32 v121, v18, v56
	v_fma_f32 v120, -v19, v56, v120
	v_fmac_f32_e32 v121, v19, v54
	v_mul_f32_e32 v122, v20, v58
	v_mul_f32_e32 v123, v20, v60
	v_fma_f32 v122, -v21, v60, v122
	v_fmac_f32_e32 v123, v21, v58
	v_mul_f32_e32 v124, v22, v62
	v_mul_f32_e32 v125, v22, v64
	v_fma_f32 v124, -v23, v64, v124
	v_fmac_f32_e32 v125, v23, v62
	v_mul_f32_e32 v126, v24, v66
	v_mul_f32_e32 v127, v24, v68
	v_fma_f32 v126, -v25, v68, v126
	v_fmac_f32_e32 v127, v25, v66
	v_mul_f32_e32 v128, v26, v70
	v_mul_f32_e32 v129, v26, v72
	v_fma_f32 v128, -v27, v72, v128
	v_fmac_f32_e32 v129, v27, v70
	v_mul_f32_e32 v130, v28, v74
	v_mul_f32_e32 v131, v28, v76
	v_fma_f32 v130, -v29, v76, v130
	v_fmac_f32_e32 v131, v29, v74
	v_mul_f32_e32 v132, v30, v78
	v_mul_f32_e32 v133, v30, v80
	v_fma_f32 v132, -v31, v80, v132
	v_fmac_f32_e32 v133, v31, v78
	v_mul_f32_e32 v134, v32, v82
	v_mul_f32_e32 v135, v32, v84
	v_fma_f32 v134, -v33, v84, v134
	v_fmac_f32_e32 v135, v33, v82
	v_mul_f32_e32 v136, v106, v86
	v_mul_f32_e32 v137, v106, v88
	v_fma_f32 v136, -v107, v88, v136
	v_fmac_f32_e32 v137, v107, v86
	v_mul_f32_e32 v138, v108, v90
	v_mul_f32_e32 v139, v108, v92
	v_fma_f32 v138, -v109, v92, v138
	v_fmac_f32_e32 v139, v109, v90
	v_mul_f32_e32 v140, v110, v94
	v_mul_f32_e32 v141, v110, v100
; template <bool INV> __device__ __forceinline__ void dft16(cf (&a)[16]) {
; #pragma unroll
;     for (int n2 = 0; n2 < 4; ++n2) dft4<INV>(a[n2], a[4 + n2], a[8 + n2], a[12 + n2]);
; #pragma unroll
;     for (int k1 = 1; k1 < 4; ++k1)
; #pragma unroll
;         for (int n2 = 1; n2 < 4; ++n2) { const cf w = {W16C(n2 * k1), W16S(n2 * k1)};
;             a[4 * k1 + n2] = INV ? cmul(a[4 * k1 + n2], w) : cmulc(a[4 * k1 + n2], w); }
; #pragma unroll
;     for (int k1 = 0; k1 < 4; ++k1) dft4<INV>(a[4 * k1 + 0], a[4 * k1 + 1], a[4 * k1 + 2], a[4 * k1 + 3]);
; }
; template <bool INV, int LQ> __device__ __forceinline__ void fft_pass16(f32x2* X, int tid) {
;     constexpr int q = 1 << LQ, STR = q + 4 * (q >> 6);
; #pragma unroll 1
;     for (int gg = 0; gg < 2; ++gg) {
;         const int g = tid + 512 * gg, blk = g >> LQ, i = g & (q - 1), base = (blk << (LQ + 4)) + i;
;         f32x2* xb = X + fidx(base);
;         cf a[16];
; #pragma unroll
;         for (int j = 0; j < 16; ++j) { const f32x2 v = xb[j * STR]; a[j] = {v.x, v.y}; }
;         const float rev = (float)i * (1.f / (float)(16 << LQ));
;         const cf w1 = {__builtin_amdgcn_cosf(rev), __builtin_amdgcn_sinf(rev)};
;         if (!INV) {
;             dft16<false>(a);
;             cf w = w1;
; #pragma unroll
;             for (int k = 1; k < 16; ++k) { const int src = 4 * (k & 3) + (k >> 2);
;                 const cf y = cmulc(a[src], w); xb[k * STR] = (f32x2){y.x, y.y}; w = cmul(w, w1); }
;             xb[0] = (f32x2){a[0].x, a[0].y};
;         } else {
;             cf w = w1;
; #pragma unroll
;             for (int k = 1; k < 16; ++k) { a[k] = cmul(a[k], w); w = cmul(w, w1); }
;             dft16<true>(a);
; #pragma unroll
;             for (int k = 0; k < 16; ++k) { const int src = 4 * (k & 3) + (k >> 2); xb[k * STR] = (f32x2){a[src].x, a[src].y}; }
;         }
	v_fma_f32 v140, -v111, v100, v140
	v_fmac_f32_e32 v141, v111, v94
	v_mul_f32_e32 v142, v112, v102
	v_mul_f32_e32 v143, v112, v104
	v_fma_f32 v142, -v113, v104, v142
	v_fmac_f32_e32 v143, v113, v102
	v_add_f32_e32 v98, v10, v128
	v_add_f32_e32 v99, v11, v129
	v_sub_f32_e32 v12, v10, v128
	v_sub_f32_e32 v13, v11, v129
	v_add_f32_e32 v14, v120, v136
	v_add_f32_e32 v15, v121, v137
	v_sub_f32_e32 v16, v120, v136
	v_sub_f32_e32 v17, v121, v137
	v_add_f32_e32 v10, v98, v14
	v_add_f32_e32 v11, v99, v15
	v_sub_f32_e32 v128, v98, v14
	v_sub_f32_e32 v129, v99, v15
	v_sub_f32_e32 v120, v12, v17
	v_add_f32_e32 v121, v13, v16
	v_add_f32_e32 v136, v12, v17
	v_sub_f32_e32 v137, v13, v16
	v_add_f32_e32 v18, v114, v130
	v_add_f32_e32 v19, v115, v131
	v_sub_f32_e32 v20, v114, v130
	v_sub_f32_e32 v21, v115, v131
	v_add_f32_e32 v22, v122, v138
	v_add_f32_e32 v23, v123, v139
	v_sub_f32_e32 v24, v122, v138
	v_sub_f32_e32 v25, v123, v139
	v_add_f32_e32 v114, v18, v22
	v_add_f32_e32 v115, v19, v23
	v_sub_f32_e32 v130, v18, v22
	v_sub_f32_e32 v131, v19, v23
	v_sub_f32_e32 v122, v20, v25
	v_add_f32_e32 v123, v21, v24
	v_add_f32_e32 v138, v20, v25
	v_sub_f32_e32 v139, v21, v24
	v_add_f32_e32 v26, v116, v132
	v_add_f32_e32 v27, v117, v133
	v_sub_f32_e32 v28, v116, v132
	v_sub_f32_e32 v29, v117, v133
	v_add_f32_e32 v30, v124, v140
	v_add_f32_e32 v31, v125, v141
	v_sub_f32_e32 v32, v124, v140
	v_sub_f32_e32 v33, v125, v141
	v_add_f32_e32 v116, v26, v30
	v_add_f32_e32 v117, v27, v31
	v_sub_f32_e32 v132, v26, v30
	v_sub_f32_e32 v133, v27, v31
	v_sub_f32_e32 v124, v28, v33
	v_add_f32_e32 v125, v29, v32
	v_add_f32_e32 v140, v28, v33
	v_sub_f32_e32 v141, v29, v32
	v_add_f32_e32 v106, v118, v134
	v_add_f32_e32 v107, v119, v135
	v_sub_f32_e32 v108, v118, v134
	v_sub_f32_e32 v109, v119, v135
	v_add_f32_e32 v110, v126, v142
	v_add_f32_e32 v111, v127, v143
	v_sub_f32_e32 v112, v126, v142
	v_sub_f32_e32 v113, v127, v143
	v_add_f32_e32 v118, v106, v110
	v_add_f32_e32 v119, v107, v111
	v_sub_f32_e32 v134, v106, v110
	v_sub_f32_e32 v135, v107, v111
	v_sub_f32_e32 v126, v108, v113
	v_add_f32_e32 v127, v109, v112
	v_add_f32_e32 v142, v108, v113
	v_sub_f32_e32 v143, v109, v112
	v_mul_f32_e32 v98, s67, v122
	v_mul_f32_e32 v99, s67, v123
	v_fma_f32 v98, -v123, s66, v98
	v_fmac_f32_e32 v99, s66, v122
	v_sub_f32_e32 v12, v124, v125
	v_add_f32_e32 v13, v124, v125
	v_mul_f32_e32 v12, s70, v12
	v_mul_f32_e32 v13, s70, v13
	v_mul_f32_e32 v14, s66, v126
	v_mul_f32_e32 v15, s66, v127
	v_fma_f32 v14, -v127, s67, v14
	v_fmac_f32_e32 v15, s67, v126
	v_sub_f32_e32 v16, v130, v131
	v_add_f32_e32 v17, v130, v131
	v_mul_f32_e32 v16, s70, v16
	v_mul_f32_e32 v17, s70, v17
	v_xor_b32_e32 v18, 0x80000000, v133
	v_mov_b32_e32 v19, v132
	v_add_f32_e32 v20, v134, v135
	v_sub_f32_e32 v21, v134, v135
	v_mul_f32_e32 v20, s71, v20
	v_mul_f32_e32 v21, s70, v21
	v_mul_f32_e32 v22, s66, v138
	v_mul_f32_e32 v23, s66, v139
	v_fma_f32 v22, -v139, s67, v22
	v_fmac_f32_e32 v23, s67, v138
	v_add_f32_e32 v24, v140, v141
	v_sub_f32_e32 v25, v140, v141
	v_mul_f32_e32 v24, s71, v24
	v_mul_f32_e32 v25, s70, v25
	v_mul_f32_e32 v26, s67, v142
	v_mul_f32_e32 v27, s67, v143
	v_fma_f32 v26, -v143, s66, v26
	v_fmac_f32_e32 v27, s66, v142
	v_xor_b32_e32 v26, 0x80000000, v26
	v_xor_b32_e32 v27, 0x80000000, v27
	v_add_f32_e32 v28, v10, v116
	v_add_f32_e32 v29, v11, v117
	v_sub_f32_e32 v30, v10, v116
	v_sub_f32_e32 v31, v11, v117
	v_add_f32_e32 v32, v114, v118
	v_add_f32_e32 v33, v115, v119
	v_sub_f32_e32 v106, v114, v118
	v_sub_f32_e32 v107, v115, v119
	v_add_f32_e32 v10, v28, v32
	v_add_f32_e32 v11, v29, v33
	v_sub_f32_e32 v116, v28, v32
	v_sub_f32_e32 v117, v29, v33
	v_sub_f32_e32 v114, v30, v107
	v_add_f32_e32 v115, v31, v106
	v_add_f32_e32 v118, v30, v107
	v_sub_f32_e32 v119, v31, v106
	v_add_f32_e32 v108, v120, v12
	v_add_f32_e32 v109, v121, v13
	v_sub_f32_e32 v110, v120, v12
	v_sub_f32_e32 v111, v121, v13
	v_add_f32_e32 v112, v98, v14
	v_add_f32_e32 v113, v99, v15
	v_sub_f32_e32 v122, v98, v14
	v_sub_f32_e32 v123, v99, v15
	v_add_f32_e32 v120, v108, v112
	v_add_f32_e32 v121, v109, v113
	v_sub_f32_e32 v12, v108, v112
	v_sub_f32_e32 v13, v109, v113
	v_sub_f32_e32 v98, v110, v123
	v_add_f32_e32 v99, v111, v122
	v_add_f32_e32 v14, v110, v123
	v_sub_f32_e32 v15, v111, v122
	v_add_f32_e32 v124, v128, v18
	v_add_f32_e32 v125, v129, v19
	v_sub_f32_e32 v126, v128, v18
	v_sub_f32_e32 v127, v129, v19
	v_add_f32_e32 v130, v16, v20
	v_add_f32_e32 v131, v17, v21
	v_sub_f32_e32 v132, v16, v20
	v_sub_f32_e32 v133, v17, v21
	v_add_f32_e32 v128, v124, v130
	v_add_f32_e32 v129, v125, v131
	v_sub_f32_e32 v18, v124, v130
	v_sub_f32_e32 v19, v125, v131
	v_sub_f32_e32 v16, v126, v133
	v_add_f32_e32 v17, v127, v132
	v_add_f32_e32 v20, v126, v133
	v_sub_f32_e32 v21, v127, v132
	v_add_f32_e32 v134, v136, v24
	v_add_f32_e32 v135, v137, v25
	v_sub_f32_e32 v138, v136, v24
	v_sub_f32_e32 v139, v137, v25
	v_add_f32_e32 v140, v22, v26
	v_add_f32_e32 v141, v23, v27
	v_sub_f32_e32 v142, v22, v26
	v_sub_f32_e32 v143, v23, v27
	v_add_f32_e32 v136, v134, v140
	v_add_f32_e32 v137, v135, v141
	v_sub_f32_e32 v24, v134, v140
	v_sub_f32_e32 v25, v135, v141
	v_sub_f32_e32 v22, v138, v143
	v_add_f32_e32 v23, v139, v142
	v_add_f32_e32 v26, v138, v143
	v_sub_f32_e32 v27, v139, v142
	ds_write_b64 v1, v[10:11]
	ds_write_b64 v1, v[120:121] offset:544
	ds_write_b64 v1, v[128:129] offset:1088
	ds_write_b64 v1, v[136:137] offset:1632
	ds_write_b64 v1, v[114:115] offset:2176
	ds_write_b64 v1, v[98:99] offset:2720
	ds_write_b64 v1, v[16:17] offset:3264
	ds_write_b64 v1, v[22:23] offset:3808
	ds_write_b64 v1, v[116:117] offset:4352
	ds_write_b64 v1, v[12:13] offset:4896
	ds_write_b64 v1, v[18:19] offset:5440
	ds_write_b64 v1, v[24:25] offset:5984
	ds_write_b64 v1, v[118:119] offset:6528
	ds_write_b64 v1, v[14:15] offset:7072
	ds_write_b64 v1, v[20:21] offset:7616
	ds_write_b64 v1, v[26:27] offset:8160
	s_mov_b32 s38, s67
	s_mov_b32 s39, s66
	s_mov_b32 s40, s70
	s_mov_b32 s41, s66
	s_mov_b32 s38, s71
	s_mov_b32 s39, s67
	s_mov_b32 s40, s25
	s_mov_b32 s41, s71
	s_movk_i32 s24, 0x2000
	s_and_b64 vcc, exec, s[0:1]
	s_mov_b64 s[0:1], 0
	s_cbranch_vccnz .LBB0_294
	s_mov_b32 s24, 0
	s_mov_b64 s[0:1], -1
	s_waitcnt lgkmcnt(0)
	s_barrier
